# A/B: attention phase without the static s_setprio 1 raise (both wave halves at priority 0); otherwise the dilated-loop peephole version
# baseline (speedup 1.0000x reference)
; __device__ __forceinline__ void attn_phase(const Params& p, unsigned char* ws, int layer, LAS unsigned char* lds, const int tid, int rep) {
;     const int wid = __builtin_amdgcn_readfirstlane(tid >> 6);
;     const bf16_t* qkv = (const bf16_t*)(ws + WS_QKV);
;     const float* kmean = (const float*)(ws + WS_KMEAN);
;     bf16_t* outA = (bf16_t*)(ws + WS_ATTA); bf16_t* outB = (bf16_t*)(ws + WS_ATTB); bf16_t* outC = (bf16_t*)(ws + WS_ATTC);
;     if (wid >= 4) __builtin_amdgcn_s_setprio(1);
.LBB0_388:
	s_andn2_b64 vcc, exec, s[0:1]
	s_cbranch_vccnz .LBB0_625
	v_readfirstlane_b32 s6, v236
	s_ashr_i32 s77, s6, 6
	s_cmp_gt_i32 s77, 3
	s_cselect_b64 s[0:1], -1, 0
	v_writelane_b32 v255, s0, 52
	s_and_b64 vcc, exec, s[0:1]
	s_nop 0
	v_writelane_b32 v255, s1, 53
	s_cbranch_vccz .LBB0_391
	s_setprio 0

; __device__ __forceinline__ void attn_phase(const Params& p, unsigned char* ws, int layer, LAS unsigned char* lds, const int tid, int rep) {
;     ...
;                 pg8::gemm_phase<EpiQKVG, OneUnit, false, GSP2>(lds, g, S1, E, t2);
;                 if (wid >= 4) __builtin_amdgcn_s_setprio(1);
;                 continue;
.LBB0_568:
	v_readlane_b32 s0, v255, 52
	v_readlane_b32 s1, v255, 53
	s_andn2_b64 vcc, exec, s[0:1]
	s_barrier
	s_cbranch_vccnz .LBB0_441
	s_setprio 0
	s_branch .LBB0_441
